# GEMM mainloops: back-edge rotation - counter/pointer SALU, exit test and back branch moved in front of the loop-closing barrier (MFMA segment tail) instead of behind it (head of the next load segment)
# baseline (speedup 1.0000x reference)
; template <class Epi>
; DI void gemm_phase(LAS unsigned char* lds, const Gemm g, const StaticOrder& S, const Epi& E) {
;     ...
;     const bool has_next = S.next(ui + 1, nxt);
;     const char* nA = has_next ? PG8_UA(nxt) : cA; const char* nB = has_next ? PG8_UB(nxt) : cB;
;     for (int t = 0; t < nt; t += 2) {
;       const bool last = (t == nt - 2);
;       const char* a1 = cA + (size_t)(t + 1) * kstep;
;       const char* a2 = last ? nA : cA + (size_t)(t + 2) * kstep; const char* b2 = last ? nB : cB + (size_t)(t + 2) * kstep;
;       const char* a3 = a2 + kstep; const char* b3 = b2 + kstep;
.LBB0_329:
	s_add_i32 vcc_lo, s46, 2
	s_add_u32 s4, s44, 0x80
	s_addc_u32 s5, s45, 0
	s_add_i32 vcc_hi, 0, 0x10000
	s_cmp_eq_u32 s63, s46
	s_cselect_b32 s47, s83, s5
	s_cselect_b32 s46, s82, s4
	s_cselect_b32 s5, s85, s49
	s_cselect_b32 s4, s84, s48
	s_add_i32 s13, 0, 0x14000
	s_branch .Lgb0
	.p2align	6

; #define PG8_STAGE(bufoff, gbase, voff) do { _Pragma("unroll") for (int _i = 0; _i < 2; ++_i) \
;     __builtin_amdgcn_global_load_lds((const unsigned*)((const char*)(gbase) + (voff)[_i]), (LAS unsigned*)(lds + (bufoff) + ldsw + _i * 8192), 16, 0, 0); } while (0)
; #define PG8_LDA(dst, b, h) do { _Pragma("unroll") for (int m = 0; m < 4; ++m) _Pragma("unroll") for (int k = 0; k < 2; ++k) dst[m][k] = *(const LAS bf16x8*)(lds + PG8_SA(b, h) + aoff + m * 2048 + k * 1024); } while (0)
; #define PG8_LDB(dst, b, h) do { _Pragma("unroll") for (int n = 0; n < 2; ++n) _Pragma("unroll") for (int k = 0; k < 2; ++k) dst[n][k] = *(const LAS bf16x8*)(lds + PG8_SB(b, h) + boff + n * 2048 + k * 1024); } while (0)
; #define PG8_MMA(ai, bj, At, Bt) do { __builtin_amdgcn_s_setprio(1); _Pragma("unroll") for (int m = 0; m < 4; ++m) _Pragma("unroll") for (int n = 0; n < 2; ++n) _Pragma("unroll") for (int k = 0; k < 2; ++k) \
;     acc[ai][bj][m][n] = __builtin_amdgcn_mfma_f32_16x16x32_bf16(Bt[n][k], At[m][k], acc[ai][bj][m][n], 0, 0, 0); __builtin_amdgcn_s_setprio(0); } while (0)
; #define PG8_WAIT_V(n) asm volatile("s_waitcnt vmcnt(" #n ")" ::: "memory")
; #define PG8_WAIT_L(n) asm volatile("s_waitcnt lgkmcnt(" #n ")" ::: "memory")
; #define PG8_BAR __builtin_amdgcn_s_barrier()
; #define PG8_SCHED __builtin_amdgcn_sched_barrier(0)
; template <class Epi>
; DI void gemm_phase(LAS unsigned char* lds, const Gemm g, const StaticOrder& S, const Epi& E) {
;     ...
;       PG8_LDB(B0, 0, 0); PG8_LDB(B1, 0, 1); PG8_SCHED; PG8_LDA(At, 0, 0); PG8_STAGE(PG8_SA(1, 1), a1 + hstepA, voffA);
;       PG8_WAIT_V(8); PG8_WAIT_L(0); PG8_BAR; PG8_MMA(0, 0, At, B0); PG8_MMA(0, 1, At, B1); PG8_BAR; PG8_SCHED;
;       PG8_LDA(At, 0, 1); PG8_STAGE(PG8_SB(0, 0), b2, voffB); PG8_STAGE(PG8_SB(0, 1), b2 + hstepB, voffB); PG8_STAGE(PG8_SA(0, 0), a2, voffA);
;       PG8_WAIT_V(8); PG8_WAIT_L(0); PG8_BAR; PG8_MMA(1, 0, At, B0); PG8_MMA(1, 1, At, B1); PG8_BAR; PG8_SCHED;
.Lgb0:
	v_add_u32_e32 v142, vcc_hi, v184
	v_add_u32_e32 v158, s13, v184
	ds_read_b128 v[130:133], v142
	ds_read_b128 v[134:137], v142 offset:1024
	ds_read_b128 v[138:141], v142 offset:2048
	ds_read_b128 v[142:145], v142 offset:3072
	ds_read_b128 v[146:149], v158
	ds_read_b128 v[150:153], v158 offset:1024
	ds_read_b128 v[154:157], v158 offset:2048
	ds_read_b128 v[158:161], v158 offset:3072
	v_lshl_add_u64 v[226:227], s[44:45], 0, v[172:173]
	s_add_i32 m0, s16, 0xc000
	ds_read_b128 v[176:179], v204
	ds_read_b128 v[180:183], v204 offset:1024
	ds_read_b128 v[206:209], v204 offset:2048
	ds_read_b128 v[210:213], v204 offset:3072
	ds_read_b128 v[214:217], v204 offset:4096
	ds_read_b128 v[218:221], v204 offset:5120
	ds_read_b128 v[222:225], v204 offset:6144
	ds_read_b128 v[230:233], v204 offset:7168
	global_load_lds_dwordx4 v[226:227], off
	v_lshl_add_u64 v[226:227], s[44:45], 0, v[174:175]
	s_add_i32 m0, s16, 0xe000
	s_nop 0
	global_load_lds_dwordx4 v[226:227], off
	s_waitcnt vmcnt(8)
	s_waitcnt lgkmcnt(0)
	s_barrier
	s_setprio 1
	s_waitcnt lgkmcnt(0)
	v_mfma_f32_16x16x32_bf16 v[126:129], v[130:133], v[176:179], v[126:129]
	v_mfma_f32_16x16x32_bf16 v[122:125], v[138:141], v[176:179], v[122:125]
	v_mfma_f32_16x16x32_bf16 v[110:113], v[130:133], v[206:209], v[110:113]
	v_mfma_f32_16x16x32_bf16 v[106:109], v[138:141], v[206:209], v[106:109]
	v_mfma_f32_16x16x32_bf16 v[94:97], v[130:133], v[214:217], v[94:97]
	v_mfma_f32_16x16x32_bf16 v[90:93], v[138:141], v[214:217], v[90:93]
	v_mfma_f32_16x16x32_bf16 v[78:81], v[130:133], v[222:225], v[78:81]
	v_mfma_f32_16x16x32_bf16 v[74:77], v[138:141], v[222:225], v[74:77]
	v_mfma_f32_16x16x32_bf16 v[126:129], v[134:137], v[180:183], v[126:129]
	v_mfma_f32_16x16x32_bf16 v[122:125], v[142:145], v[180:183], v[122:125]
	v_mfma_f32_16x16x32_bf16 v[110:113], v[134:137], v[210:213], v[110:113]
	v_mfma_f32_16x16x32_bf16 v[106:109], v[142:145], v[210:213], v[106:109]
	v_mfma_f32_16x16x32_bf16 v[94:97], v[134:137], v[218:221], v[94:97]
	v_mfma_f32_16x16x32_bf16 v[90:93], v[142:145], v[218:221], v[90:93]
	v_mfma_f32_16x16x32_bf16 v[78:81], v[134:137], v[230:233], v[78:81]
	v_mfma_f32_16x16x32_bf16 v[74:77], v[142:145], v[230:233], v[74:77]
	s_setprio 0
	s_setprio 1
	v_mfma_f32_16x16x32_bf16 v[118:121], v[146:149], v[176:179], v[118:121]
	v_mfma_f32_16x16x32_bf16 v[114:117], v[154:157], v[176:179], v[114:117]
	v_mfma_f32_16x16x32_bf16 v[102:105], v[146:149], v[206:209], v[102:105]
	v_mfma_f32_16x16x32_bf16 v[98:101], v[154:157], v[206:209], v[98:101]
	v_mfma_f32_16x16x32_bf16 v[86:89], v[146:149], v[214:217], v[86:89]
	v_mfma_f32_16x16x32_bf16 v[82:85], v[154:157], v[214:217], v[82:85]
	v_mfma_f32_16x16x32_bf16 v[70:73], v[146:149], v[222:225], v[70:73]
	v_mfma_f32_16x16x32_bf16 v[66:69], v[154:157], v[222:225], v[66:69]
	v_mfma_f32_16x16x32_bf16 v[118:121], v[150:153], v[180:183], v[118:121]
	v_mfma_f32_16x16x32_bf16 v[114:117], v[158:161], v[180:183], v[114:117]
	v_mfma_f32_16x16x32_bf16 v[102:105], v[150:153], v[210:213], v[102:105]
	v_mfma_f32_16x16x32_bf16 v[98:101], v[158:161], v[210:213], v[98:101]
	v_mfma_f32_16x16x32_bf16 v[86:89], v[150:153], v[218:221], v[86:89]
	v_mfma_f32_16x16x32_bf16 v[82:85], v[158:161], v[218:221], v[82:85]
	v_mfma_f32_16x16x32_bf16 v[70:73], v[150:153], v[230:233], v[70:73]
	v_mfma_f32_16x16x32_bf16 v[66:69], v[158:161], v[230:233], v[66:69]
	s_setprio 0
	s_barrier
	s_add_i32 vcc_hi, vcc_hi, s3
	v_lshl_add_u64 v[226:227], s[4:5], 0, v[0:1]
	s_mov_b32 m0, vcc_hi
	ds_read_b128 v[176:179], v204 offset:16384
	ds_read_b128 v[180:183], v204 offset:17408
	ds_read_b128 v[206:209], v204 offset:18432
	ds_read_b128 v[210:213], v204 offset:19456
	ds_read_b128 v[214:217], v204 offset:20480
	ds_read_b128 v[218:221], v204 offset:21504
	ds_read_b128 v[222:225], v204 offset:22528
	ds_read_b128 v[230:233], v204 offset:23552
	global_load_lds_dwordx4 v[226:227], off
	s_add_i32 m0, vcc_hi, 0x2000
	v_lshl_add_u64 v[234:235], s[4:5], 0, v[170:171]
	s_add_u32 s4, s4, s10
	s_addc_u32 s5, s5, s11
	s_add_i32 s13, s13, s3
	global_load_lds_dwordx4 v[234:235], off
	v_lshl_add_u64 v[236:237], s[4:5], 0, v[0:1]
	s_mov_b32 m0, s13
	v_lshl_add_u64 v[238:239], s[4:5], 0, v[170:171]
	global_load_lds_dwordx4 v[236:237], off
	s_add_i32 m0, s13, 0x2000
	v_lshl_add_u64 v[240:241], s[46:47], 0, v[166:167]
	global_load_lds_dwordx4 v[238:239], off
	s_mov_b32 m0, s16
	v_lshl_add_u64 v[242:243], s[46:47], 0, v[168:169]
	global_load_lds_dwordx4 v[240:241], off
	s_mov_b32 m0, s17
	s_nop 0
	global_load_lds_dwordx4 v[242:243], off
	s_waitcnt vmcnt(8)
	s_waitcnt lgkmcnt(0)
	s_barrier
; #define PG8_STAGE(bufoff, gbase, voff) do { _Pragma("unroll") for (int _i = 0; _i < 2; ++_i) \
;     __builtin_amdgcn_global_load_lds((const unsigned*)((const char*)(gbase) + (voff)[_i]), (LAS unsigned*)(lds + (bufoff) + ldsw + _i * 8192), 16, 0, 0); } while (0)
; #define PG8_LDA(dst, b, h) do { _Pragma("unroll") for (int m = 0; m < 4; ++m) _Pragma("unroll") for (int k = 0; k < 2; ++k) dst[m][k] = *(const LAS bf16x8*)(lds + PG8_SA(b, h) + aoff + m * 2048 + k * 1024); } while (0)
; #define PG8_LDB(dst, b, h) do { _Pragma("unroll") for (int n = 0; n < 2; ++n) _Pragma("unroll") for (int k = 0; k < 2; ++k) dst[n][k] = *(const LAS bf16x8*)(lds + PG8_SB(b, h) + boff + n * 2048 + k * 1024); } while (0)
; #define PG8_MMA(ai, bj, At, Bt) do { __builtin_amdgcn_s_setprio(1); _Pragma("unroll") for (int m = 0; m < 4; ++m) _Pragma("unroll") for (int n = 0; n < 2; ++n) _Pragma("unroll") for (int k = 0; k < 2; ++k) \
;     acc[ai][bj][m][n] = __builtin_amdgcn_mfma_f32_16x16x32_bf16(Bt[n][k], At[m][k], acc[ai][bj][m][n], 0, 0, 0); __builtin_amdgcn_s_setprio(0); } while (0)
; #define PG8_WAIT_V(n) asm volatile("s_waitcnt vmcnt(" #n ")" ::: "memory")
; #define PG8_WAIT_L(n) asm volatile("s_waitcnt lgkmcnt(" #n ")" ::: "memory")
; #define PG8_BAR __builtin_amdgcn_s_barrier()
; #define PG8_SCHED __builtin_amdgcn_sched_barrier(0)
; template <class Epi>
; DI void gemm_phase(LAS unsigned char* lds, const Gemm g, const StaticOrder& S, const Epi& E) {
;     ...
;       PG8_WAIT_V(8); PG8_WAIT_L(0); PG8_BAR; PG8_MMA(1, 0, At, B0); PG8_MMA(1, 1, At, B1); PG8_BAR; PG8_SCHED;
;       PG8_LDB(B0, 1, 0); PG8_LDB(B1, 1, 1); PG8_SCHED; PG8_LDA(At, 1, 0); PG8_STAGE(PG8_SA(0, 1), a2 + hstepA, voffA);
;       PG8_WAIT_V(8); PG8_WAIT_L(0); PG8_BAR; PG8_MMA(0, 0, At, B0); PG8_MMA(0, 1, At, B1); PG8_BAR; PG8_SCHED;
	s_setprio 1
	s_waitcnt lgkmcnt(0)
	v_mfma_f32_16x16x32_bf16 v[62:65], v[130:133], v[176:179], v[62:65]
	v_mfma_f32_16x16x32_bf16 v[58:61], v[138:141], v[176:179], v[58:61]
	v_mfma_f32_16x16x32_bf16 v[46:49], v[130:133], v[206:209], v[46:49]
	v_mfma_f32_16x16x32_bf16 v[42:45], v[138:141], v[206:209], v[42:45]
	v_mfma_f32_16x16x32_bf16 v[30:33], v[130:133], v[214:217], v[30:33]
	v_mfma_f32_16x16x32_bf16 v[26:29], v[138:141], v[214:217], v[26:29]
	v_mfma_f32_16x16x32_bf16 v[14:17], v[130:133], v[222:225], v[14:17]
	v_mfma_f32_16x16x32_bf16 v[10:13], v[138:141], v[222:225], v[10:13]
	v_mfma_f32_16x16x32_bf16 v[62:65], v[134:137], v[180:183], v[62:65]
	v_mfma_f32_16x16x32_bf16 v[58:61], v[142:145], v[180:183], v[58:61]
	v_mfma_f32_16x16x32_bf16 v[46:49], v[134:137], v[210:213], v[46:49]
	v_mfma_f32_16x16x32_bf16 v[42:45], v[142:145], v[210:213], v[42:45]
	v_mfma_f32_16x16x32_bf16 v[30:33], v[134:137], v[218:221], v[30:33]
	v_mfma_f32_16x16x32_bf16 v[26:29], v[142:145], v[218:221], v[26:29]
	v_mfma_f32_16x16x32_bf16 v[14:17], v[134:137], v[230:233], v[14:17]
	v_mfma_f32_16x16x32_bf16 v[10:13], v[142:145], v[230:233], v[10:13]
	s_setprio 0
	s_setprio 1
	v_mfma_f32_16x16x32_bf16 v[54:57], v[146:149], v[176:179], v[54:57]
	v_mfma_f32_16x16x32_bf16 v[50:53], v[154:157], v[176:179], v[50:53]
	v_mfma_f32_16x16x32_bf16 v[38:41], v[146:149], v[206:209], v[38:41]
	v_mfma_f32_16x16x32_bf16 v[34:37], v[154:157], v[206:209], v[34:37]
	v_mfma_f32_16x16x32_bf16 v[22:25], v[146:149], v[214:217], v[22:25]
	v_mfma_f32_16x16x32_bf16 v[18:21], v[154:157], v[214:217], v[18:21]
	v_mfma_f32_16x16x32_bf16 v[6:9], v[146:149], v[222:225], v[6:9]
	v_mfma_f32_16x16x32_bf16 v[2:5], v[154:157], v[222:225], v[2:5]
	v_mfma_f32_16x16x32_bf16 v[54:57], v[150:153], v[180:183], v[54:57]
	v_mfma_f32_16x16x32_bf16 v[50:53], v[158:161], v[180:183], v[50:53]
	v_mfma_f32_16x16x32_bf16 v[38:41], v[150:153], v[210:213], v[38:41]
	v_mfma_f32_16x16x32_bf16 v[34:37], v[158:161], v[210:213], v[34:37]
	v_mfma_f32_16x16x32_bf16 v[22:25], v[150:153], v[218:221], v[22:25]
	v_mfma_f32_16x16x32_bf16 v[18:21], v[158:161], v[218:221], v[18:21]
	v_mfma_f32_16x16x32_bf16 v[6:9], v[150:153], v[230:233], v[6:9]
	v_mfma_f32_16x16x32_bf16 v[2:5], v[158:161], v[230:233], v[2:5]
	s_setprio 0
	s_barrier
	s_add_i32 s13, 0, 0x18000
	s_add_i32 vcc_hi, 0, 0x1c000
	v_add_u32_e32 v142, s13, v184
	v_add_u32_e32 v158, vcc_hi, v184
	ds_read_b128 v[130:133], v142
	ds_read_b128 v[134:137], v142 offset:1024
	ds_read_b128 v[138:141], v142 offset:2048
	ds_read_b128 v[142:145], v142 offset:3072
	ds_read_b128 v[146:149], v158
	ds_read_b128 v[150:153], v158 offset:1024
	ds_read_b128 v[154:157], v158 offset:2048
	ds_read_b128 v[158:161], v158 offset:3072
	s_add_u32 s4, s46, s8
	s_addc_u32 s5, s47, s9
	s_mov_b32 m0, s33
	v_lshl_add_u64 v[244:245], s[4:5], 0, v[166:167]
	ds_read_b128 v[176:179], v204 offset:32768
	ds_read_b128 v[180:183], v204 offset:33792
	ds_read_b128 v[206:209], v204 offset:34816
	ds_read_b128 v[210:213], v204 offset:35840
	ds_read_b128 v[214:217], v204 offset:36864
	ds_read_b128 v[218:221], v204 offset:37888
	ds_read_b128 v[222:225], v204 offset:38912
	ds_read_b128 v[230:233], v204 offset:39936
	global_load_lds_dwordx4 v[244:245], off
	v_lshl_add_u64 v[244:245], s[4:5], 0, v[168:169]
	s_mov_b32 m0, s56
	s_nop 0
	global_load_lds_dwordx4 v[244:245], off
	s_waitcnt vmcnt(8)
	s_waitcnt lgkmcnt(0)
	s_barrier
	s_setprio 1
	s_waitcnt lgkmcnt(0)
	v_mfma_f32_16x16x32_bf16 v[126:129], v[130:133], v[176:179], v[126:129]
	v_mfma_f32_16x16x32_bf16 v[122:125], v[138:141], v[176:179], v[122:125]
	v_mfma_f32_16x16x32_bf16 v[110:113], v[130:133], v[206:209], v[110:113]
	v_mfma_f32_16x16x32_bf16 v[106:109], v[138:141], v[206:209], v[106:109]
	v_mfma_f32_16x16x32_bf16 v[94:97], v[130:133], v[214:217], v[94:97]
	v_mfma_f32_16x16x32_bf16 v[90:93], v[138:141], v[214:217], v[90:93]
	v_mfma_f32_16x16x32_bf16 v[78:81], v[130:133], v[222:225], v[78:81]
	v_mfma_f32_16x16x32_bf16 v[74:77], v[138:141], v[222:225], v[74:77]
	v_mfma_f32_16x16x32_bf16 v[126:129], v[134:137], v[180:183], v[126:129]
	v_mfma_f32_16x16x32_bf16 v[122:125], v[142:145], v[180:183], v[122:125]
	v_mfma_f32_16x16x32_bf16 v[110:113], v[134:137], v[210:213], v[110:113]
	v_mfma_f32_16x16x32_bf16 v[106:109], v[142:145], v[210:213], v[106:109]
	v_mfma_f32_16x16x32_bf16 v[94:97], v[134:137], v[218:221], v[94:97]
	v_mfma_f32_16x16x32_bf16 v[90:93], v[142:145], v[218:221], v[90:93]
	v_mfma_f32_16x16x32_bf16 v[78:81], v[134:137], v[230:233], v[78:81]
	v_mfma_f32_16x16x32_bf16 v[74:77], v[142:145], v[230:233], v[74:77]
	s_setprio 0
	s_setprio 1
	v_mfma_f32_16x16x32_bf16 v[118:121], v[146:149], v[176:179], v[118:121]
	v_mfma_f32_16x16x32_bf16 v[114:117], v[154:157], v[176:179], v[114:117]
	v_mfma_f32_16x16x32_bf16 v[102:105], v[146:149], v[206:209], v[102:105]
	v_mfma_f32_16x16x32_bf16 v[98:101], v[154:157], v[206:209], v[98:101]
	v_mfma_f32_16x16x32_bf16 v[86:89], v[146:149], v[214:217], v[86:89]
	v_mfma_f32_16x16x32_bf16 v[82:85], v[154:157], v[214:217], v[82:85]
	v_mfma_f32_16x16x32_bf16 v[70:73], v[146:149], v[222:225], v[70:73]
	v_mfma_f32_16x16x32_bf16 v[66:69], v[154:157], v[222:225], v[66:69]
	v_mfma_f32_16x16x32_bf16 v[118:121], v[150:153], v[180:183], v[118:121]
	v_mfma_f32_16x16x32_bf16 v[114:117], v[158:161], v[180:183], v[114:117]
	v_mfma_f32_16x16x32_bf16 v[102:105], v[150:153], v[210:213], v[102:105]
	v_mfma_f32_16x16x32_bf16 v[98:101], v[158:161], v[210:213], v[98:101]
	v_mfma_f32_16x16x32_bf16 v[86:89], v[150:153], v[218:221], v[86:89]
	v_mfma_f32_16x16x32_bf16 v[82:85], v[158:161], v[218:221], v[82:85]
	v_mfma_f32_16x16x32_bf16 v[70:73], v[150:153], v[230:233], v[70:73]
	v_mfma_f32_16x16x32_bf16 v[66:69], v[158:161], v[230:233], v[66:69]
	s_setprio 0
	s_barrier
; #define PG8_STAGE(bufoff, gbase, voff) do { _Pragma("unroll") for (int _i = 0; _i < 2; ++_i) \
;     __builtin_amdgcn_global_load_lds((const unsigned*)((const char*)(gbase) + (voff)[_i]), (LAS unsigned*)(lds + (bufoff) + ldsw + _i * 8192), 16, 0, 0); } while (0)
; #define PG8_LDA(dst, b, h) do { _Pragma("unroll") for (int m = 0; m < 4; ++m) _Pragma("unroll") for (int k = 0; k < 2; ++k) dst[m][k] = *(const LAS bf16x8*)(lds + PG8_SA(b, h) + aoff + m * 2048 + k * 1024); } while (0)
; #define PG8_MMA(ai, bj, At, Bt) do { __builtin_amdgcn_s_setprio(1); _Pragma("unroll") for (int m = 0; m < 4; ++m) _Pragma("unroll") for (int n = 0; n < 2; ++n) _Pragma("unroll") for (int k = 0; k < 2; ++k) \
;     acc[ai][bj][m][n] = __builtin_amdgcn_mfma_f32_16x16x32_bf16(Bt[n][k], At[m][k], acc[ai][bj][m][n], 0, 0, 0); __builtin_amdgcn_s_setprio(0); } while (0)
; #define PG8_WAIT_V(n) asm volatile("s_waitcnt vmcnt(" #n ")" ::: "memory")
; #define PG8_WAIT_L(n) asm volatile("s_waitcnt lgkmcnt(" #n ")" ::: "memory")
; #define PG8_BAR __builtin_amdgcn_s_barrier()
; #define PG8_SCHED __builtin_amdgcn_sched_barrier(0)
; template <class Epi>
; DI void gemm_phase(LAS unsigned char* lds, const Gemm g, const StaticOrder& S, const Epi& E) {
;     ...
;     for (int t = 0; t < nt; t += 2) {
;     ...
;       PG8_LDA(At, 1, 1); PG8_STAGE(PG8_SB(1, 0), b3, voffB); PG8_STAGE(PG8_SB(1, 1), b3 + hstepB, voffB); PG8_STAGE(PG8_SA(1, 0), a3, voffA);
;       PG8_WAIT_V(8); PG8_WAIT_L(0); PG8_BAR; PG8_MMA(1, 0, At, B0); PG8_MMA(1, 1, At, B1); PG8_BAR; PG8_SCHED;
;     }
;     if (wr == 0) PG8_BAR;
	s_add_i32 s4, s13, s3
	v_lshl_add_u64 v[226:227], v[226:227], 0, s[38:39]
	s_mov_b32 m0, s4
	ds_read_b128 v[176:179], v204 offset:49152
	ds_read_b128 v[180:183], v204 offset:50176
	ds_read_b128 v[206:209], v204 offset:51200
	ds_read_b128 v[210:213], v204 offset:52224
	ds_read_b128 v[214:217], v204 offset:53248
	ds_read_b128 v[218:221], v204 offset:54272
	ds_read_b128 v[222:225], v204 offset:55296
	ds_read_b128 v[230:233], v204 offset:56320
	global_load_lds_dwordx4 v[226:227], off
	v_lshl_add_u64 v[226:227], v[234:235], 0, s[38:39]
	s_add_i32 m0, s4, 0x2000
	s_add_i32 s4, vcc_hi, s3
	global_load_lds_dwordx4 v[226:227], off
	v_lshl_add_u64 v[226:227], v[236:237], 0, s[38:39]
	s_mov_b32 m0, s4
	s_nop 0
	global_load_lds_dwordx4 v[226:227], off
	v_lshl_add_u64 v[226:227], v[238:239], 0, s[38:39]
	s_add_i32 m0, s4, 0x2000
	s_nop 0
	global_load_lds_dwordx4 v[226:227], off
	v_lshl_add_u64 v[226:227], v[240:241], 0, s[38:39]
	s_mov_b32 m0, s58
	s_nop 0
	global_load_lds_dwordx4 v[226:227], off
	v_lshl_add_u64 v[226:227], v[242:243], 0, s[38:39]
	s_mov_b32 m0, s62
	s_nop 0
	global_load_lds_dwordx4 v[226:227], off
	s_waitcnt vmcnt(8)
	s_waitcnt lgkmcnt(0)
	s_barrier
	s_setprio 1
	s_waitcnt lgkmcnt(0)
	v_mfma_f32_16x16x32_bf16 v[62:65], v[130:133], v[176:179], v[62:65]
	v_mfma_f32_16x16x32_bf16 v[58:61], v[138:141], v[176:179], v[58:61]
	v_mfma_f32_16x16x32_bf16 v[46:49], v[130:133], v[206:209], v[46:49]
	v_mfma_f32_16x16x32_bf16 v[42:45], v[138:141], v[206:209], v[42:45]
	v_mfma_f32_16x16x32_bf16 v[30:33], v[130:133], v[214:217], v[30:33]
	v_mfma_f32_16x16x32_bf16 v[26:29], v[138:141], v[214:217], v[26:29]
	v_mfma_f32_16x16x32_bf16 v[14:17], v[130:133], v[222:225], v[14:17]
	v_mfma_f32_16x16x32_bf16 v[10:13], v[138:141], v[222:225], v[10:13]
	v_mfma_f32_16x16x32_bf16 v[62:65], v[134:137], v[180:183], v[62:65]
	v_mfma_f32_16x16x32_bf16 v[58:61], v[142:145], v[180:183], v[58:61]
	v_mfma_f32_16x16x32_bf16 v[46:49], v[134:137], v[210:213], v[46:49]
	v_mfma_f32_16x16x32_bf16 v[42:45], v[142:145], v[210:213], v[42:45]
	v_mfma_f32_16x16x32_bf16 v[30:33], v[134:137], v[218:221], v[30:33]
	v_mfma_f32_16x16x32_bf16 v[26:29], v[142:145], v[218:221], v[26:29]
	v_mfma_f32_16x16x32_bf16 v[14:17], v[134:137], v[230:233], v[14:17]
	v_mfma_f32_16x16x32_bf16 v[10:13], v[142:145], v[230:233], v[10:13]
	s_setprio 0
	s_setprio 1
	v_mfma_f32_16x16x32_bf16 v[54:57], v[146:149], v[176:179], v[54:57]
	v_mfma_f32_16x16x32_bf16 v[50:53], v[154:157], v[176:179], v[50:53]
	v_mfma_f32_16x16x32_bf16 v[38:41], v[146:149], v[206:209], v[38:41]
	v_mfma_f32_16x16x32_bf16 v[34:37], v[154:157], v[206:209], v[34:37]
	v_mfma_f32_16x16x32_bf16 v[22:25], v[146:149], v[214:217], v[22:25]
	v_mfma_f32_16x16x32_bf16 v[18:21], v[154:157], v[214:217], v[18:21]
	v_mfma_f32_16x16x32_bf16 v[6:9], v[146:149], v[222:225], v[6:9]
	v_mfma_f32_16x16x32_bf16 v[2:5], v[154:157], v[222:225], v[2:5]
	v_mfma_f32_16x16x32_bf16 v[54:57], v[150:153], v[180:183], v[54:57]
	v_mfma_f32_16x16x32_bf16 v[50:53], v[158:161], v[180:183], v[50:53]
	v_mfma_f32_16x16x32_bf16 v[38:41], v[150:153], v[210:213], v[38:41]
	v_mfma_f32_16x16x32_bf16 v[34:37], v[158:161], v[210:213], v[34:37]
	v_mfma_f32_16x16x32_bf16 v[22:25], v[150:153], v[218:221], v[22:25]
	v_mfma_f32_16x16x32_bf16 v[18:21], v[158:161], v[218:221], v[18:21]
	v_mfma_f32_16x16x32_bf16 v[6:9], v[150:153], v[230:233], v[6:9]
	v_mfma_f32_16x16x32_bf16 v[2:5], v[158:161], v[230:233], v[2:5]
	s_setprio 0
	s_add_u32 s44, s44, 0x100
	s_addc_u32 s45, s45, 0
	s_add_u32 s48, s48, 0x100
	s_addc_u32 s49, s49, 0
	s_cmp_ge_i32 vcc_lo, s57
	s_mov_b32 s46, vcc_lo
	s_cbranch_scc1 .Lgx0
	s_add_i32 vcc_lo, s46, 2
	s_add_u32 s4, s44, 0x80
	s_addc_u32 s5, s45, 0
	s_add_i32 vcc_hi, 0, 0x10000
	s_cmp_eq_u32 s63, s46
	s_cselect_b32 s47, s83, s5
	s_cselect_b32 s46, s82, s4
	s_cselect_b32 s5, s85, s49
	s_cselect_b32 s4, s84, s48
	s_add_i32 s13, 0, 0x14000
	s_branch .Lgr0
.Lgx0:
	s_barrier
.LBB0_330:
	s_and_b64 vcc, exec, s[22:23]
	s_cbranch_vccz .LBB0_332
	s_barrier

; template <class Epi>
; DI void gemm_phase(LAS unsigned char* lds, const Gemm g, const StaticOrder& S, const Epi& E) {
;     ...
;     const bool has_next = S.next(ui + 1, nxt);
;     const char* nA = has_next ? PG8_UA(nxt) : cA; const char* nB = has_next ? PG8_UB(nxt) : cB;
;     for (int t = 0; t < nt; t += 2) {
;       const bool last = (t == nt - 2);
;       const char* a1 = cA + (size_t)(t + 1) * kstep;
;       const char* a2 = last ? nA : cA + (size_t)(t + 2) * kstep; const char* b2 = last ? nB : cB + (size_t)(t + 2) * kstep;
;       const char* a3 = a2 + kstep; const char* b3 = b2 + kstep;
.LBB0_555:
	s_add_i32 s87, s54, 2
	s_add_u32 s88, s42, 0x80
	s_addc_u32 s55, s43, 0
	s_add_i32 s94, 0, 0x10000
	s_cmp_eq_u32 s69, s54
	s_cselect_b32 s55, s21, s55
	s_cselect_b32 s54, s20, s88
	s_cselect_b32 s89, s23, s63
	s_cselect_b32 s88, s22, s62
	s_add_i32 s95, 0, 0x14000
	s_branch .Lgb1
	.p2align	6

; #define PG8_STAGE(bufoff, gbase, voff) do { _Pragma("unroll") for (int _i = 0; _i < 2; ++_i) \
;     __builtin_amdgcn_global_load_lds((const unsigned*)((const char*)(gbase) + (voff)[_i]), (LAS unsigned*)(lds + (bufoff) + ldsw + _i * 8192), 16, 0, 0); } while (0)
; #define PG8_LDA(dst, b, h) do { _Pragma("unroll") for (int m = 0; m < 4; ++m) _Pragma("unroll") for (int k = 0; k < 2; ++k) dst[m][k] = *(const LAS bf16x8*)(lds + PG8_SA(b, h) + aoff + m * 2048 + k * 1024); } while (0)
; #define PG8_LDB(dst, b, h) do { _Pragma("unroll") for (int n = 0; n < 2; ++n) _Pragma("unroll") for (int k = 0; k < 2; ++k) dst[n][k] = *(const LAS bf16x8*)(lds + PG8_SB(b, h) + boff + n * 2048 + k * 1024); } while (0)
; #define PG8_MMA(ai, bj, At, Bt) do { __builtin_amdgcn_s_setprio(1); _Pragma("unroll") for (int m = 0; m < 4; ++m) _Pragma("unroll") for (int n = 0; n < 2; ++n) _Pragma("unroll") for (int k = 0; k < 2; ++k) \
;     acc[ai][bj][m][n] = __builtin_amdgcn_mfma_f32_16x16x32_bf16(Bt[n][k], At[m][k], acc[ai][bj][m][n], 0, 0, 0); __builtin_amdgcn_s_setprio(0); } while (0)
; #define PG8_WAIT_V(n) asm volatile("s_waitcnt vmcnt(" #n ")" ::: "memory")
; #define PG8_WAIT_L(n) asm volatile("s_waitcnt lgkmcnt(" #n ")" ::: "memory")
; #define PG8_BAR __builtin_amdgcn_s_barrier()
; #define PG8_SCHED __builtin_amdgcn_sched_barrier(0)
; template <class Epi>
; DI void gemm_phase(LAS unsigned char* lds, const Gemm g, const StaticOrder& S, const Epi& E) {
;     ...
;       PG8_LDB(B0, 0, 0); PG8_LDB(B1, 0, 1); PG8_SCHED; PG8_LDA(At, 0, 0); PG8_STAGE(PG8_SA(1, 1), a1 + hstepA, voffA);
;       PG8_WAIT_V(8); PG8_WAIT_L(0); PG8_BAR; PG8_MMA(0, 0, At, B0); PG8_MMA(0, 1, At, B1); PG8_BAR; PG8_SCHED;
;       PG8_LDA(At, 0, 1); PG8_STAGE(PG8_SB(0, 0), b2, voffB); PG8_STAGE(PG8_SB(0, 1), b2 + hstepB, voffB); PG8_STAGE(PG8_SA(0, 0), a2, voffA);
;       PG8_WAIT_V(8); PG8_WAIT_L(0); PG8_BAR; PG8_MMA(1, 0, At, B0); PG8_MMA(1, 1, At, B1); PG8_BAR; PG8_SCHED;
.Lgb1:
	v_add_u32_e32 v54, s94, v182
	v_add_u32_e32 v158, s95, v182
	ds_read_b128 v[34:37], v54
	ds_read_b128 v[42:45], v54 offset:1024
	ds_read_b128 v[50:53], v54 offset:2048
	ds_read_b128 v[54:57], v54 offset:3072
	ds_read_b128 v[62:65], v158
	ds_read_b128 v[66:69], v158 offset:1024
	ds_read_b128 v[154:157], v158 offset:2048
	ds_read_b128 v[158:161], v158 offset:3072
	v_lshl_add_u64 v[180:181], s[42:43], 0, v[172:173]
	s_add_i32 m0, s16, 0xc000
	ds_read_b128 v[176:179], v184
	ds_read_b128 v[204:207], v184 offset:1024
	ds_read_b128 v[208:211], v184 offset:2048
	ds_read_b128 v[212:215], v184 offset:3072
	ds_read_b128 v[216:219], v184 offset:4096
	ds_read_b128 v[220:223], v184 offset:5120
	ds_read_b128 v[224:227], v184 offset:6144
	ds_read_b128 v[230:233], v184 offset:7168
	global_load_lds_dwordx4 v[180:181], off
	v_lshl_add_u64 v[180:181], s[42:43], 0, v[174:175]
	s_add_i32 m0, s16, 0xe000
	s_nop 0
	global_load_lds_dwordx4 v[180:181], off
	s_waitcnt vmcnt(8)
	s_waitcnt lgkmcnt(0)
	s_barrier
	s_setprio 1
	s_waitcnt lgkmcnt(0)
	v_mfma_f32_16x16x32_bf16 v[150:153], v[34:37], v[176:179], v[150:153]
	v_mfma_f32_16x16x32_bf16 v[146:149], v[50:53], v[176:179], v[146:149]
	v_mfma_f32_16x16x32_bf16 v[134:137], v[34:37], v[208:211], v[134:137]
	v_mfma_f32_16x16x32_bf16 v[130:133], v[50:53], v[208:211], v[130:133]
	v_mfma_f32_16x16x32_bf16 v[118:121], v[34:37], v[216:219], v[118:121]
	v_mfma_f32_16x16x32_bf16 v[114:117], v[50:53], v[216:219], v[114:117]
	v_mfma_f32_16x16x32_bf16 v[102:105], v[34:37], v[224:227], v[102:105]
	v_mfma_f32_16x16x32_bf16 v[98:101], v[50:53], v[224:227], v[98:101]
	v_mfma_f32_16x16x32_bf16 v[150:153], v[42:45], v[204:207], v[150:153]
	v_mfma_f32_16x16x32_bf16 v[146:149], v[54:57], v[204:207], v[146:149]
	v_mfma_f32_16x16x32_bf16 v[134:137], v[42:45], v[212:215], v[134:137]
	v_mfma_f32_16x16x32_bf16 v[130:133], v[54:57], v[212:215], v[130:133]
	v_mfma_f32_16x16x32_bf16 v[118:121], v[42:45], v[220:223], v[118:121]
	v_mfma_f32_16x16x32_bf16 v[114:117], v[54:57], v[220:223], v[114:117]
	v_mfma_f32_16x16x32_bf16 v[102:105], v[42:45], v[230:233], v[102:105]
	v_mfma_f32_16x16x32_bf16 v[98:101], v[54:57], v[230:233], v[98:101]
	s_setprio 0
	s_setprio 1
	v_mfma_f32_16x16x32_bf16 v[138:141], v[62:65], v[176:179], v[138:141]
	v_mfma_f32_16x16x32_bf16 v[142:145], v[154:157], v[176:179], v[142:145]
	v_mfma_f32_16x16x32_bf16 v[122:125], v[62:65], v[208:211], v[122:125]
	v_mfma_f32_16x16x32_bf16 v[126:129], v[154:157], v[208:211], v[126:129]
	v_mfma_f32_16x16x32_bf16 v[106:109], v[62:65], v[216:219], v[106:109]
	v_mfma_f32_16x16x32_bf16 v[110:113], v[154:157], v[216:219], v[110:113]
	v_mfma_f32_16x16x32_bf16 v[90:93], v[62:65], v[224:227], v[90:93]
	v_mfma_f32_16x16x32_bf16 v[94:97], v[154:157], v[224:227], v[94:97]
	v_mfma_f32_16x16x32_bf16 v[138:141], v[66:69], v[204:207], v[138:141]
	v_mfma_f32_16x16x32_bf16 v[142:145], v[158:161], v[204:207], v[142:145]
	v_mfma_f32_16x16x32_bf16 v[122:125], v[66:69], v[212:215], v[122:125]
	v_mfma_f32_16x16x32_bf16 v[126:129], v[158:161], v[212:215], v[126:129]
	v_mfma_f32_16x16x32_bf16 v[106:109], v[66:69], v[220:223], v[106:109]
	v_mfma_f32_16x16x32_bf16 v[110:113], v[158:161], v[220:223], v[110:113]
	v_mfma_f32_16x16x32_bf16 v[90:93], v[66:69], v[230:233], v[90:93]
	v_mfma_f32_16x16x32_bf16 v[94:97], v[158:161], v[230:233], v[94:97]
	s_setprio 0
	s_barrier
	s_add_i32 s94, s94, s3
	v_lshl_add_u64 v[180:181], s[88:89], 0, v[0:1]
	s_mov_b32 m0, s94
	ds_read_b128 v[176:179], v184 offset:16384
	ds_read_b128 v[204:207], v184 offset:17408
	ds_read_b128 v[208:211], v184 offset:18432
	ds_read_b128 v[212:215], v184 offset:19456
	ds_read_b128 v[216:219], v184 offset:20480
	ds_read_b128 v[220:223], v184 offset:21504
	ds_read_b128 v[224:227], v184 offset:22528
	ds_read_b128 v[230:233], v184 offset:23552
	global_load_lds_dwordx4 v[180:181], off
	s_add_i32 m0, s94, 0x2000
	v_lshl_add_u64 v[238:239], s[88:89], 0, v[170:171]
	s_add_u32 s88, s88, s6
	s_addc_u32 s89, s89, s7
	s_add_i32 s94, s95, s3
	global_load_lds_dwordx4 v[238:239], off
	v_lshl_add_u64 v[240:241], s[88:89], 0, v[0:1]
	s_mov_b32 m0, s94
	v_lshl_add_u64 v[242:243], s[88:89], 0, v[170:171]
	global_load_lds_dwordx4 v[240:241], off
	s_add_i32 m0, s94, 0x2000
	v_lshl_add_u64 v[244:245], s[54:55], 0, v[166:167]
	global_load_lds_dwordx4 v[242:243], off
	s_mov_b32 m0, s16
	v_lshl_add_u64 v[246:247], s[54:55], 0, v[168:169]
	global_load_lds_dwordx4 v[244:245], off
	s_mov_b32 m0, s17
	s_nop 0
	global_load_lds_dwordx4 v[246:247], off
	s_waitcnt vmcnt(8)
	s_waitcnt lgkmcnt(0)
	s_barrier
; #define PG8_STAGE(bufoff, gbase, voff) do { _Pragma("unroll") for (int _i = 0; _i < 2; ++_i) \
;     __builtin_amdgcn_global_load_lds((const unsigned*)((const char*)(gbase) + (voff)[_i]), (LAS unsigned*)(lds + (bufoff) + ldsw + _i * 8192), 16, 0, 0); } while (0)
; #define PG8_LDA(dst, b, h) do { _Pragma("unroll") for (int m = 0; m < 4; ++m) _Pragma("unroll") for (int k = 0; k < 2; ++k) dst[m][k] = *(const LAS bf16x8*)(lds + PG8_SA(b, h) + aoff + m * 2048 + k * 1024); } while (0)
; #define PG8_LDB(dst, b, h) do { _Pragma("unroll") for (int n = 0; n < 2; ++n) _Pragma("unroll") for (int k = 0; k < 2; ++k) dst[n][k] = *(const LAS bf16x8*)(lds + PG8_SB(b, h) + boff + n * 2048 + k * 1024); } while (0)
; #define PG8_MMA(ai, bj, At, Bt) do { __builtin_amdgcn_s_setprio(1); _Pragma("unroll") for (int m = 0; m < 4; ++m) _Pragma("unroll") for (int n = 0; n < 2; ++n) _Pragma("unroll") for (int k = 0; k < 2; ++k) \
;     acc[ai][bj][m][n] = __builtin_amdgcn_mfma_f32_16x16x32_bf16(Bt[n][k], At[m][k], acc[ai][bj][m][n], 0, 0, 0); __builtin_amdgcn_s_setprio(0); } while (0)
; #define PG8_WAIT_V(n) asm volatile("s_waitcnt vmcnt(" #n ")" ::: "memory")
; #define PG8_WAIT_L(n) asm volatile("s_waitcnt lgkmcnt(" #n ")" ::: "memory")
; #define PG8_BAR __builtin_amdgcn_s_barrier()
; #define PG8_SCHED __builtin_amdgcn_sched_barrier(0)
; template <class Epi>
; DI void gemm_phase(LAS unsigned char* lds, const Gemm g, const StaticOrder& S, const Epi& E) {
;     ...
;       PG8_WAIT_V(8); PG8_WAIT_L(0); PG8_BAR; PG8_MMA(1, 0, At, B0); PG8_MMA(1, 1, At, B1); PG8_BAR; PG8_SCHED;
;       PG8_LDB(B0, 1, 0); PG8_LDB(B1, 1, 1); PG8_SCHED; PG8_LDA(At, 1, 0); PG8_STAGE(PG8_SA(0, 1), a2 + hstepA, voffA);
;       PG8_WAIT_V(8); PG8_WAIT_L(0); PG8_BAR; PG8_MMA(0, 0, At, B0); PG8_MMA(0, 1, At, B1); PG8_BAR; PG8_SCHED;
	s_setprio 1
	s_waitcnt lgkmcnt(0)
	v_mfma_f32_16x16x32_bf16 v[86:89], v[34:37], v[176:179], v[86:89]
	v_mfma_f32_16x16x32_bf16 v[82:85], v[50:53], v[176:179], v[82:85]
	v_mfma_f32_16x16x32_bf16 v[70:73], v[34:37], v[208:211], v[70:73]
	v_mfma_f32_16x16x32_bf16 v[58:61], v[50:53], v[208:211], v[58:61]
	v_mfma_f32_16x16x32_bf16 v[30:33], v[34:37], v[216:219], v[30:33]
	v_mfma_f32_16x16x32_bf16 v[26:29], v[50:53], v[216:219], v[26:29]
	v_mfma_f32_16x16x32_bf16 v[14:17], v[34:37], v[224:227], v[14:17]
	v_mfma_f32_16x16x32_bf16 v[10:13], v[50:53], v[224:227], v[10:13]
	v_mfma_f32_16x16x32_bf16 v[86:89], v[42:45], v[204:207], v[86:89]
	v_mfma_f32_16x16x32_bf16 v[82:85], v[54:57], v[204:207], v[82:85]
	v_mfma_f32_16x16x32_bf16 v[70:73], v[42:45], v[212:215], v[70:73]
	v_mfma_f32_16x16x32_bf16 v[58:61], v[54:57], v[212:215], v[58:61]
	v_mfma_f32_16x16x32_bf16 v[30:33], v[42:45], v[220:223], v[30:33]
	v_mfma_f32_16x16x32_bf16 v[26:29], v[54:57], v[220:223], v[26:29]
	v_mfma_f32_16x16x32_bf16 v[14:17], v[42:45], v[230:233], v[14:17]
	v_mfma_f32_16x16x32_bf16 v[10:13], v[54:57], v[230:233], v[10:13]
	s_setprio 0
	s_setprio 1
	v_mfma_f32_16x16x32_bf16 v[38:41], v[62:65], v[208:211], v[38:41]
	v_mfma_f32_16x16x32_bf16 v[46:49], v[154:157], v[208:211], v[46:49]
	v_mfma_f32_16x16x32_bf16 v[18:21], v[62:65], v[216:219], v[18:21]
	v_mfma_f32_16x16x32_bf16 v[22:25], v[154:157], v[216:219], v[22:25]
	v_mfma_f32_16x16x32_bf16 v[2:5], v[62:65], v[224:227], v[2:5]
	v_mfma_f32_16x16x32_bf16 v[6:9], v[154:157], v[224:227], v[6:9]
	v_mfma_f32_16x16x32_bf16 v[34:37], v[62:65], v[176:179], v[74:77]
	v_mfma_f32_16x16x32_bf16 v[42:45], v[154:157], v[176:179], v[78:81]
	v_mfma_f32_16x16x32_bf16 v[38:41], v[66:69], v[212:215], v[38:41]
	v_mfma_f32_16x16x32_bf16 v[46:49], v[158:161], v[212:215], v[46:49]
	v_mfma_f32_16x16x32_bf16 v[18:21], v[66:69], v[220:223], v[18:21]
	v_mfma_f32_16x16x32_bf16 v[22:25], v[158:161], v[220:223], v[22:25]
	v_mfma_f32_16x16x32_bf16 v[2:5], v[66:69], v[230:233], v[2:5]
	v_mfma_f32_16x16x32_bf16 v[6:9], v[158:161], v[230:233], v[6:9]
	v_mfma_f32_16x16x32_bf16 v[34:37], v[66:69], v[204:207], v[34:37]
	v_mfma_f32_16x16x32_bf16 v[42:45], v[158:161], v[204:207], v[42:45]
	s_setprio 0
	s_barrier
	s_add_i32 s88, 0, 0x18000
	s_add_i32 s89, 0, 0x1c000
	v_add_u32_e32 v66, s88, v182
	v_add_u32_e32 v74, s89, v182
	ds_read_b128 v[50:53], v66
	ds_read_b128 v[54:57], v66 offset:1024
	ds_read_b128 v[62:65], v66 offset:2048
	ds_read_b128 v[66:69], v66 offset:3072
	ds_read_b128 v[154:157], v74
	ds_read_b128 v[158:161], v74 offset:1024
	ds_read_b128 v[176:179], v74 offset:2048
	ds_read_b128 v[204:207], v74 offset:3072
	s_add_u32 s54, s54, s4
	s_addc_u32 s55, s55, s5
	s_mov_b32 m0, s33
	v_lshl_add_u64 v[234:235], s[54:55], 0, v[166:167]
	ds_read_b128 v[74:77], v184 offset:32768
	ds_read_b128 v[78:81], v184 offset:33792
	ds_read_b128 v[208:211], v184 offset:34816
	ds_read_b128 v[212:215], v184 offset:35840
	ds_read_b128 v[216:219], v184 offset:36864
	ds_read_b128 v[220:223], v184 offset:37888
	ds_read_b128 v[224:227], v184 offset:38912
	ds_read_b128 v[230:233], v184 offset:39936
	global_load_lds_dwordx4 v[234:235], off
	v_lshl_add_u64 v[234:235], s[54:55], 0, v[168:169]
	s_mov_b32 m0, s56
	s_nop 0
	global_load_lds_dwordx4 v[234:235], off
	s_waitcnt vmcnt(8)
	s_waitcnt lgkmcnt(0)
	s_barrier
	s_setprio 1
	s_waitcnt lgkmcnt(0)
	v_mfma_f32_16x16x32_bf16 v[150:153], v[50:53], v[74:77], v[150:153]
	v_mfma_f32_16x16x32_bf16 v[146:149], v[62:65], v[74:77], v[146:149]
	v_mfma_f32_16x16x32_bf16 v[134:137], v[50:53], v[208:211], v[134:137]
	v_mfma_f32_16x16x32_bf16 v[130:133], v[62:65], v[208:211], v[130:133]
	v_mfma_f32_16x16x32_bf16 v[118:121], v[50:53], v[216:219], v[118:121]
	v_mfma_f32_16x16x32_bf16 v[114:117], v[62:65], v[216:219], v[114:117]
	v_mfma_f32_16x16x32_bf16 v[102:105], v[50:53], v[224:227], v[102:105]
	v_mfma_f32_16x16x32_bf16 v[98:101], v[62:65], v[224:227], v[98:101]
	v_mfma_f32_16x16x32_bf16 v[150:153], v[54:57], v[78:81], v[150:153]
	v_mfma_f32_16x16x32_bf16 v[146:149], v[66:69], v[78:81], v[146:149]
	v_mfma_f32_16x16x32_bf16 v[134:137], v[54:57], v[212:215], v[134:137]
	v_mfma_f32_16x16x32_bf16 v[130:133], v[66:69], v[212:215], v[130:133]
	v_mfma_f32_16x16x32_bf16 v[118:121], v[54:57], v[220:223], v[118:121]
	v_mfma_f32_16x16x32_bf16 v[114:117], v[66:69], v[220:223], v[114:117]
	v_mfma_f32_16x16x32_bf16 v[102:105], v[54:57], v[230:233], v[102:105]
	v_mfma_f32_16x16x32_bf16 v[98:101], v[66:69], v[230:233], v[98:101]
	s_setprio 0
	s_setprio 1
	v_mfma_f32_16x16x32_bf16 v[138:141], v[154:157], v[74:77], v[138:141]
	v_mfma_f32_16x16x32_bf16 v[74:77], v[176:179], v[74:77], v[142:145]
	v_mfma_f32_16x16x32_bf16 v[142:145], v[204:207], v[78:81], v[74:77]
	v_mfma_f32_16x16x32_bf16 v[74:77], v[154:157], v[208:211], v[122:125]
	v_mfma_f32_16x16x32_bf16 v[122:125], v[158:161], v[212:215], v[74:77]
	v_mfma_f32_16x16x32_bf16 v[74:77], v[176:179], v[208:211], v[126:129]
	v_mfma_f32_16x16x32_bf16 v[126:129], v[204:207], v[212:215], v[74:77]
	v_mfma_f32_16x16x32_bf16 v[74:77], v[154:157], v[216:219], v[106:109]
	v_mfma_f32_16x16x32_bf16 v[106:109], v[158:161], v[220:223], v[74:77]
	v_mfma_f32_16x16x32_bf16 v[74:77], v[176:179], v[216:219], v[110:113]
	v_mfma_f32_16x16x32_bf16 v[110:113], v[204:207], v[220:223], v[74:77]
	v_mfma_f32_16x16x32_bf16 v[74:77], v[154:157], v[224:227], v[90:93]
	v_mfma_f32_16x16x32_bf16 v[90:93], v[158:161], v[230:233], v[74:77]
	v_mfma_f32_16x16x32_bf16 v[74:77], v[176:179], v[224:227], v[94:97]
	v_mfma_f32_16x16x32_bf16 v[138:141], v[158:161], v[78:81], v[138:141]
	v_mfma_f32_16x16x32_bf16 v[94:97], v[204:207], v[230:233], v[74:77]
	s_setprio 0
	s_barrier
; #define PG8_STAGE(bufoff, gbase, voff) do { _Pragma("unroll") for (int _i = 0; _i < 2; ++_i) \
;     __builtin_amdgcn_global_load_lds((const unsigned*)((const char*)(gbase) + (voff)[_i]), (LAS unsigned*)(lds + (bufoff) + ldsw + _i * 8192), 16, 0, 0); } while (0)
; #define PG8_LDA(dst, b, h) do { _Pragma("unroll") for (int m = 0; m < 4; ++m) _Pragma("unroll") for (int k = 0; k < 2; ++k) dst[m][k] = *(const LAS bf16x8*)(lds + PG8_SA(b, h) + aoff + m * 2048 + k * 1024); } while (0)
; #define PG8_MMA(ai, bj, At, Bt) do { __builtin_amdgcn_s_setprio(1); _Pragma("unroll") for (int m = 0; m < 4; ++m) _Pragma("unroll") for (int n = 0; n < 2; ++n) _Pragma("unroll") for (int k = 0; k < 2; ++k) \
;     acc[ai][bj][m][n] = __builtin_amdgcn_mfma_f32_16x16x32_bf16(Bt[n][k], At[m][k], acc[ai][bj][m][n], 0, 0, 0); __builtin_amdgcn_s_setprio(0); } while (0)
; #define PG8_WAIT_V(n) asm volatile("s_waitcnt vmcnt(" #n ")" ::: "memory")
; #define PG8_WAIT_L(n) asm volatile("s_waitcnt lgkmcnt(" #n ")" ::: "memory")
; #define PG8_BAR __builtin_amdgcn_s_barrier()
; #define PG8_SCHED __builtin_amdgcn_sched_barrier(0)
; template <class Epi>
; DI void gemm_phase(LAS unsigned char* lds, const Gemm g, const StaticOrder& S, const Epi& E) {
;     ...
;     for (int t = 0; t < nt; t += 2) {
;     ...
;       PG8_LDA(At, 1, 1); PG8_STAGE(PG8_SB(1, 0), b3, voffB); PG8_STAGE(PG8_SB(1, 1), b3 + hstepB, voffB); PG8_STAGE(PG8_SA(1, 0), a3, voffA);
;       PG8_WAIT_V(8); PG8_WAIT_L(0); PG8_BAR; PG8_MMA(1, 0, At, B0); PG8_MMA(1, 1, At, B1); PG8_BAR; PG8_SCHED;
;     }
;     if (wr == 0) PG8_BAR;
	s_add_i32 s54, s88, s3
	s_nop 2
	v_lshl_add_u64 v[74:75], v[180:181], 0, s[38:39]
	s_mov_b32 m0, s54
	ds_read_b128 v[78:81], v184 offset:49152
	ds_read_b128 v[208:211], v184 offset:50176
	ds_read_b128 v[212:215], v184 offset:51200
	ds_read_b128 v[216:219], v184 offset:52224
	ds_read_b128 v[220:223], v184 offset:53248
	ds_read_b128 v[224:227], v184 offset:54272
	ds_read_b128 v[230:233], v184 offset:55296
	ds_read_b128 v[234:237], v184 offset:56320
	global_load_lds_dwordx4 v[74:75], off
	v_lshl_add_u64 v[74:75], v[238:239], 0, s[38:39]
	s_add_i32 m0, s54, 0x2000
	s_add_i32 s54, s89, s3
	global_load_lds_dwordx4 v[74:75], off
	v_lshl_add_u64 v[74:75], v[240:241], 0, s[38:39]
	s_mov_b32 m0, s54
	s_nop 0
	global_load_lds_dwordx4 v[74:75], off
	v_lshl_add_u64 v[74:75], v[242:243], 0, s[38:39]
	s_add_i32 m0, s54, 0x2000
	s_nop 0
	global_load_lds_dwordx4 v[74:75], off
	v_lshl_add_u64 v[74:75], v[244:245], 0, s[38:39]
	s_mov_b32 m0, s58
	s_nop 0
	global_load_lds_dwordx4 v[74:75], off
	v_lshl_add_u64 v[74:75], v[246:247], 0, s[38:39]
	s_mov_b32 m0, s68
	s_nop 0
	global_load_lds_dwordx4 v[74:75], off
	s_waitcnt vmcnt(8)
	s_waitcnt lgkmcnt(0)
	s_barrier
	s_setprio 1
	s_waitcnt lgkmcnt(0)
	v_mfma_f32_16x16x32_bf16 v[74:77], v[50:53], v[78:81], v[86:89]
	v_mfma_f32_16x16x32_bf16 v[86:89], v[54:57], v[208:211], v[74:77]
	v_mfma_f32_16x16x32_bf16 v[74:77], v[62:65], v[78:81], v[82:85]
	v_mfma_f32_16x16x32_bf16 v[70:73], v[50:53], v[212:215], v[70:73]
	v_mfma_f32_16x16x32_bf16 v[58:61], v[62:65], v[212:215], v[58:61]
	v_mfma_f32_16x16x32_bf16 v[30:33], v[50:53], v[220:223], v[30:33]
	v_mfma_f32_16x16x32_bf16 v[26:29], v[62:65], v[220:223], v[26:29]
	v_mfma_f32_16x16x32_bf16 v[14:17], v[50:53], v[230:233], v[14:17]
	v_mfma_f32_16x16x32_bf16 v[10:13], v[62:65], v[230:233], v[10:13]
	v_mfma_f32_16x16x32_bf16 v[82:85], v[66:69], v[208:211], v[74:77]
	v_mfma_f32_16x16x32_bf16 v[70:73], v[54:57], v[216:219], v[70:73]
	v_mfma_f32_16x16x32_bf16 v[58:61], v[66:69], v[216:219], v[58:61]
	v_mfma_f32_16x16x32_bf16 v[30:33], v[54:57], v[224:227], v[30:33]
	v_mfma_f32_16x16x32_bf16 v[26:29], v[66:69], v[224:227], v[26:29]
	v_mfma_f32_16x16x32_bf16 v[14:17], v[54:57], v[234:237], v[14:17]
	v_mfma_f32_16x16x32_bf16 v[10:13], v[66:69], v[234:237], v[10:13]
	s_setprio 0
	s_setprio 1
	v_mfma_f32_16x16x32_bf16 v[34:37], v[154:157], v[78:81], v[34:37]
	v_mfma_f32_16x16x32_bf16 v[74:77], v[158:161], v[208:211], v[34:37]
	v_mfma_f32_16x16x32_bf16 v[34:37], v[176:179], v[78:81], v[42:45]
	v_mfma_f32_16x16x32_bf16 v[78:81], v[204:207], v[208:211], v[34:37]
	v_mfma_f32_16x16x32_bf16 v[34:37], v[154:157], v[212:215], v[38:41]
	v_mfma_f32_16x16x32_bf16 v[38:41], v[158:161], v[216:219], v[34:37]
	v_mfma_f32_16x16x32_bf16 v[34:37], v[176:179], v[212:215], v[46:49]
	v_mfma_f32_16x16x32_bf16 v[18:21], v[154:157], v[220:223], v[18:21]
	v_mfma_f32_16x16x32_bf16 v[22:25], v[176:179], v[220:223], v[22:25]
	v_mfma_f32_16x16x32_bf16 v[2:5], v[154:157], v[230:233], v[2:5]
	v_mfma_f32_16x16x32_bf16 v[6:9], v[176:179], v[230:233], v[6:9]
	v_mfma_f32_16x16x32_bf16 v[46:49], v[204:207], v[216:219], v[34:37]
	v_mfma_f32_16x16x32_bf16 v[18:21], v[158:161], v[224:227], v[18:21]
	v_mfma_f32_16x16x32_bf16 v[22:25], v[204:207], v[224:227], v[22:25]
	v_mfma_f32_16x16x32_bf16 v[2:5], v[158:161], v[234:237], v[2:5]
	v_mfma_f32_16x16x32_bf16 v[6:9], v[204:207], v[234:237], v[6:9]
	s_setprio 0
	s_add_u32 s42, s42, 0x100
	s_addc_u32 s43, s43, 0
	s_add_u32 s62, s62, 0x100
	s_addc_u32 s63, s63, 0
	s_cmp_ge_i32 s87, s57
	s_mov_b32 s54, s87
	s_cbranch_scc1 .Lgx1
	s_add_i32 s87, s54, 2
	s_add_u32 s88, s42, 0x80
	s_addc_u32 s55, s43, 0
	s_add_i32 s94, 0, 0x10000
	s_cmp_eq_u32 s69, s54
	s_cselect_b32 s55, s21, s55
	s_cselect_b32 s54, s20, s88
	s_cselect_b32 s89, s23, s63
	s_cselect_b32 s88, s22, s62
	s_add_i32 s95, 0, 0x14000
	s_branch .Lgr1
.Lgx1:
	s_barrier
	s_movk_i32 s88, 0xc00

; template <class Epi>
; DI void gemm_phase(LAS unsigned char* lds, const Gemm g, const StaticOrder& S, const Epi& E) {
;     ...
;     const bool has_next = S.next(ui + 1, nxt);
;     const char* nA = has_next ? PG8_UA(nxt) : cA; const char* nB = has_next ? PG8_UB(nxt) : cB;
;     for (int t = 0; t < nt; t += 2) {
;       const bool last = (t == nt - 2);
;       const char* a1 = cA + (size_t)(t + 1) * kstep;
;       const char* a2 = last ? nA : cA + (size_t)(t + 2) * kstep; const char* b2 = last ? nB : cB + (size_t)(t + 2) * kstep;
;       const char* a3 = a2 + kstep; const char* b3 = b2 + kstep;
.LBB0_844:
	s_add_i32 s49, s46, 2
	s_add_u32 s50, s44, 0x80
	s_addc_u32 s47, s45, 0
	s_add_i32 s52, 0, 0x10000
	s_cmp_eq_u32 s33, s46
	s_cselect_b32 s47, s13, s47
	s_cselect_b32 s46, s12, s50
	s_cselect_b32 s51, s85, s48
	s_cselect_b32 s50, s84, s23
	s_add_i32 s53, 0, 0x14000
	s_branch .Lgb2
	.p2align	6

; #define PG8_STAGE(bufoff, gbase, voff) do { _Pragma("unroll") for (int _i = 0; _i < 2; ++_i) \
;     __builtin_amdgcn_global_load_lds((const unsigned*)((const char*)(gbase) + (voff)[_i]), (LAS unsigned*)(lds + (bufoff) + ldsw + _i * 8192), 16, 0, 0); } while (0)
; #define PG8_LDA(dst, b, h) do { _Pragma("unroll") for (int m = 0; m < 4; ++m) _Pragma("unroll") for (int k = 0; k < 2; ++k) dst[m][k] = *(const LAS bf16x8*)(lds + PG8_SA(b, h) + aoff + m * 2048 + k * 1024); } while (0)
; #define PG8_LDB(dst, b, h) do { _Pragma("unroll") for (int n = 0; n < 2; ++n) _Pragma("unroll") for (int k = 0; k < 2; ++k) dst[n][k] = *(const LAS bf16x8*)(lds + PG8_SB(b, h) + boff + n * 2048 + k * 1024); } while (0)
; #define PG8_MMA(ai, bj, At, Bt) do { __builtin_amdgcn_s_setprio(1); _Pragma("unroll") for (int m = 0; m < 4; ++m) _Pragma("unroll") for (int n = 0; n < 2; ++n) _Pragma("unroll") for (int k = 0; k < 2; ++k) \
;     acc[ai][bj][m][n] = __builtin_amdgcn_mfma_f32_16x16x32_bf16(Bt[n][k], At[m][k], acc[ai][bj][m][n], 0, 0, 0); __builtin_amdgcn_s_setprio(0); } while (0)
; #define PG8_WAIT_V(n) asm volatile("s_waitcnt vmcnt(" #n ")" ::: "memory")
; #define PG8_WAIT_L(n) asm volatile("s_waitcnt lgkmcnt(" #n ")" ::: "memory")
; #define PG8_BAR __builtin_amdgcn_s_barrier()
; #define PG8_SCHED __builtin_amdgcn_sched_barrier(0)
; template <class Epi>
; DI void gemm_phase(LAS unsigned char* lds, const Gemm g, const StaticOrder& S, const Epi& E) {
;     ...
;       PG8_LDB(B0, 0, 0); PG8_LDB(B1, 0, 1); PG8_SCHED; PG8_LDA(At, 0, 0); PG8_STAGE(PG8_SA(1, 1), a1 + hstepA, voffA);
;       PG8_WAIT_V(8); PG8_WAIT_L(0); PG8_BAR; PG8_MMA(0, 0, At, B0); PG8_MMA(0, 1, At, B1); PG8_BAR; PG8_SCHED;
;       PG8_LDA(At, 0, 1); PG8_STAGE(PG8_SB(0, 0), b2, voffB); PG8_STAGE(PG8_SB(0, 1), b2 + hstepB, voffB); PG8_STAGE(PG8_SA(0, 0), a2, voffA);
;       PG8_WAIT_V(8); PG8_WAIT_L(0); PG8_BAR; PG8_MMA(1, 0, At, B0); PG8_MMA(1, 1, At, B1); PG8_BAR; PG8_SCHED;
.Lgb2:
	v_add_u32_e32 v156, s52, v178
	v_add_u32_e32 v160, s53, v178
	ds_read_b128 v[130:133], v156
	ds_read_b128 v[134:137], v156 offset:1024
	ds_read_b128 v[152:155], v156 offset:2048
	ds_read_b128 v[156:159], v156 offset:3072
	ds_read_b128 v[166:169], v160
	ds_read_b128 v[170:173], v160 offset:1024
	ds_read_b128 v[174:177], v160 offset:2048
	ds_read_b128 v[182:185], v160 offset:3072
	v_lshl_add_u64 v[160:161], s[44:45], 0, v[148:149]
	s_add_i32 m0, s54, 0xc000
	ds_read_b128 v[204:207], v180
	ds_read_b128 v[208:211], v180 offset:1024
	ds_read_b128 v[212:215], v180 offset:2048
	ds_read_b128 v[216:219], v180 offset:3072
	ds_read_b128 v[220:223], v180 offset:4096
	ds_read_b128 v[224:227], v180 offset:5120
	ds_read_b128 v[230:233], v180 offset:6144
	ds_read_b128 v[234:237], v180 offset:7168
	global_load_lds_dwordx4 v[160:161], off
	v_lshl_add_u64 v[160:161], s[44:45], 0, v[150:151]
	s_add_i32 m0, s54, 0xe000
	s_nop 0
	global_load_lds_dwordx4 v[160:161], off
	s_waitcnt vmcnt(8)
	s_waitcnt lgkmcnt(0)
	s_barrier
	s_setprio 1
	s_waitcnt lgkmcnt(0)
	v_mfma_f32_16x16x32_bf16 v[126:129], v[130:133], v[204:207], v[126:129]
	v_mfma_f32_16x16x32_bf16 v[122:125], v[152:155], v[204:207], v[122:125]
	v_mfma_f32_16x16x32_bf16 v[110:113], v[130:133], v[212:215], v[110:113]
	v_mfma_f32_16x16x32_bf16 v[106:109], v[152:155], v[212:215], v[106:109]
	v_mfma_f32_16x16x32_bf16 v[94:97], v[130:133], v[220:223], v[94:97]
	v_mfma_f32_16x16x32_bf16 v[90:93], v[152:155], v[220:223], v[90:93]
	v_mfma_f32_16x16x32_bf16 v[78:81], v[130:133], v[230:233], v[78:81]
	v_mfma_f32_16x16x32_bf16 v[74:77], v[152:155], v[230:233], v[74:77]
	v_mfma_f32_16x16x32_bf16 v[126:129], v[134:137], v[208:211], v[126:129]
	v_mfma_f32_16x16x32_bf16 v[122:125], v[156:159], v[208:211], v[122:125]
	v_mfma_f32_16x16x32_bf16 v[110:113], v[134:137], v[216:219], v[110:113]
	v_mfma_f32_16x16x32_bf16 v[106:109], v[156:159], v[216:219], v[106:109]
	v_mfma_f32_16x16x32_bf16 v[94:97], v[134:137], v[224:227], v[94:97]
	v_mfma_f32_16x16x32_bf16 v[90:93], v[156:159], v[224:227], v[90:93]
	v_mfma_f32_16x16x32_bf16 v[78:81], v[134:137], v[234:237], v[78:81]
	v_mfma_f32_16x16x32_bf16 v[74:77], v[156:159], v[234:237], v[74:77]
	s_setprio 0
	s_setprio 1
	v_mfma_f32_16x16x32_bf16 v[118:121], v[166:169], v[204:207], v[118:121]
	v_mfma_f32_16x16x32_bf16 v[114:117], v[174:177], v[204:207], v[114:117]
	v_mfma_f32_16x16x32_bf16 v[102:105], v[166:169], v[212:215], v[102:105]
	v_mfma_f32_16x16x32_bf16 v[98:101], v[174:177], v[212:215], v[98:101]
	v_mfma_f32_16x16x32_bf16 v[86:89], v[166:169], v[220:223], v[86:89]
	v_mfma_f32_16x16x32_bf16 v[82:85], v[174:177], v[220:223], v[82:85]
	v_mfma_f32_16x16x32_bf16 v[70:73], v[166:169], v[230:233], v[70:73]
	v_mfma_f32_16x16x32_bf16 v[66:69], v[174:177], v[230:233], v[66:69]
	v_mfma_f32_16x16x32_bf16 v[118:121], v[170:173], v[208:211], v[118:121]
	v_mfma_f32_16x16x32_bf16 v[114:117], v[182:185], v[208:211], v[114:117]
	v_mfma_f32_16x16x32_bf16 v[102:105], v[170:173], v[216:219], v[102:105]
	v_mfma_f32_16x16x32_bf16 v[98:101], v[182:185], v[216:219], v[98:101]
	v_mfma_f32_16x16x32_bf16 v[86:89], v[170:173], v[224:227], v[86:89]
	v_mfma_f32_16x16x32_bf16 v[82:85], v[182:185], v[224:227], v[82:85]
	v_mfma_f32_16x16x32_bf16 v[70:73], v[170:173], v[234:237], v[70:73]
	v_mfma_f32_16x16x32_bf16 v[66:69], v[182:185], v[234:237], v[66:69]
	s_setprio 0
	s_barrier
	s_add_i32 s52, s52, s17
	v_lshl_add_u64 v[160:161], s[50:51], 0, v[140:141]
	s_mov_b32 m0, s52
	ds_read_b128 v[204:207], v180 offset:16384
	ds_read_b128 v[208:211], v180 offset:17408
	ds_read_b128 v[212:215], v180 offset:18432
	ds_read_b128 v[216:219], v180 offset:19456
	ds_read_b128 v[220:223], v180 offset:20480
	ds_read_b128 v[224:227], v180 offset:21504
	ds_read_b128 v[230:233], v180 offset:22528
	ds_read_b128 v[234:237], v180 offset:23552
	global_load_lds_dwordx4 v[160:161], off
	s_add_i32 m0, s52, 0x2000
	v_lshl_add_u64 v[238:239], s[50:51], 0, v[144:145]
	s_add_u32 s50, s50, s94
	s_addc_u32 s51, s51, s95
	s_add_i32 s52, s53, s17
	global_load_lds_dwordx4 v[238:239], off
	v_lshl_add_u64 v[240:241], s[50:51], 0, v[140:141]
	s_mov_b32 m0, s52
	v_lshl_add_u64 v[242:243], s[50:51], 0, v[144:145]
	global_load_lds_dwordx4 v[240:241], off
	s_add_i32 m0, s52, 0x2000
	v_lshl_add_u64 v[244:245], s[46:47], 0, v[138:139]
	global_load_lds_dwordx4 v[242:243], off
	s_mov_b32 m0, s54
	v_lshl_add_u64 v[246:247], s[46:47], 0, v[142:143]
	global_load_lds_dwordx4 v[244:245], off
	s_mov_b32 m0, s55
	s_nop 0
	global_load_lds_dwordx4 v[246:247], off
	s_waitcnt vmcnt(8)
	s_waitcnt lgkmcnt(0)
	s_barrier
; #define PG8_STAGE(bufoff, gbase, voff) do { _Pragma("unroll") for (int _i = 0; _i < 2; ++_i) \
;     __builtin_amdgcn_global_load_lds((const unsigned*)((const char*)(gbase) + (voff)[_i]), (LAS unsigned*)(lds + (bufoff) + ldsw + _i * 8192), 16, 0, 0); } while (0)
; #define PG8_LDA(dst, b, h) do { _Pragma("unroll") for (int m = 0; m < 4; ++m) _Pragma("unroll") for (int k = 0; k < 2; ++k) dst[m][k] = *(const LAS bf16x8*)(lds + PG8_SA(b, h) + aoff + m * 2048 + k * 1024); } while (0)
; #define PG8_LDB(dst, b, h) do { _Pragma("unroll") for (int n = 0; n < 2; ++n) _Pragma("unroll") for (int k = 0; k < 2; ++k) dst[n][k] = *(const LAS bf16x8*)(lds + PG8_SB(b, h) + boff + n * 2048 + k * 1024); } while (0)
; #define PG8_MMA(ai, bj, At, Bt) do { __builtin_amdgcn_s_setprio(1); _Pragma("unroll") for (int m = 0; m < 4; ++m) _Pragma("unroll") for (int n = 0; n < 2; ++n) _Pragma("unroll") for (int k = 0; k < 2; ++k) \
;     acc[ai][bj][m][n] = __builtin_amdgcn_mfma_f32_16x16x32_bf16(Bt[n][k], At[m][k], acc[ai][bj][m][n], 0, 0, 0); __builtin_amdgcn_s_setprio(0); } while (0)
; #define PG8_WAIT_V(n) asm volatile("s_waitcnt vmcnt(" #n ")" ::: "memory")
; #define PG8_WAIT_L(n) asm volatile("s_waitcnt lgkmcnt(" #n ")" ::: "memory")
; #define PG8_BAR __builtin_amdgcn_s_barrier()
; #define PG8_SCHED __builtin_amdgcn_sched_barrier(0)
; template <class Epi>
; DI void gemm_phase(LAS unsigned char* lds, const Gemm g, const StaticOrder& S, const Epi& E) {
;     ...
;       PG8_WAIT_V(8); PG8_WAIT_L(0); PG8_BAR; PG8_MMA(1, 0, At, B0); PG8_MMA(1, 1, At, B1); PG8_BAR; PG8_SCHED;
;       PG8_LDB(B0, 1, 0); PG8_LDB(B1, 1, 1); PG8_SCHED; PG8_LDA(At, 1, 0); PG8_STAGE(PG8_SA(0, 1), a2 + hstepA, voffA);
;       PG8_WAIT_V(8); PG8_WAIT_L(0); PG8_BAR; PG8_MMA(0, 0, At, B0); PG8_MMA(0, 1, At, B1); PG8_BAR; PG8_SCHED;
	s_setprio 1
	s_waitcnt lgkmcnt(0)
	v_mfma_f32_16x16x32_bf16 v[62:65], v[130:133], v[204:207], v[62:65]
	v_mfma_f32_16x16x32_bf16 v[58:61], v[152:155], v[204:207], v[58:61]
	v_mfma_f32_16x16x32_bf16 v[46:49], v[130:133], v[212:215], v[46:49]
	v_mfma_f32_16x16x32_bf16 v[42:45], v[152:155], v[212:215], v[42:45]
	v_mfma_f32_16x16x32_bf16 v[30:33], v[130:133], v[220:223], v[30:33]
	v_mfma_f32_16x16x32_bf16 v[26:29], v[152:155], v[220:223], v[26:29]
	v_mfma_f32_16x16x32_bf16 v[14:17], v[130:133], v[230:233], v[14:17]
	v_mfma_f32_16x16x32_bf16 v[10:13], v[152:155], v[230:233], v[10:13]
	v_mfma_f32_16x16x32_bf16 v[62:65], v[134:137], v[208:211], v[62:65]
	v_mfma_f32_16x16x32_bf16 v[58:61], v[156:159], v[208:211], v[58:61]
	v_mfma_f32_16x16x32_bf16 v[46:49], v[134:137], v[216:219], v[46:49]
	v_mfma_f32_16x16x32_bf16 v[42:45], v[156:159], v[216:219], v[42:45]
	v_mfma_f32_16x16x32_bf16 v[30:33], v[134:137], v[224:227], v[30:33]
	v_mfma_f32_16x16x32_bf16 v[26:29], v[156:159], v[224:227], v[26:29]
	v_mfma_f32_16x16x32_bf16 v[14:17], v[134:137], v[234:237], v[14:17]
	v_mfma_f32_16x16x32_bf16 v[10:13], v[156:159], v[234:237], v[10:13]
	s_setprio 0
	s_setprio 1
	v_mfma_f32_16x16x32_bf16 v[54:57], v[166:169], v[204:207], v[54:57]
	v_mfma_f32_16x16x32_bf16 v[50:53], v[174:177], v[204:207], v[50:53]
	v_mfma_f32_16x16x32_bf16 v[38:41], v[166:169], v[212:215], v[38:41]
	v_mfma_f32_16x16x32_bf16 v[34:37], v[174:177], v[212:215], v[34:37]
	v_mfma_f32_16x16x32_bf16 v[22:25], v[166:169], v[220:223], v[22:25]
	v_mfma_f32_16x16x32_bf16 v[18:21], v[174:177], v[220:223], v[18:21]
	v_mfma_f32_16x16x32_bf16 v[6:9], v[166:169], v[230:233], v[6:9]
	v_mfma_f32_16x16x32_bf16 v[2:5], v[174:177], v[230:233], v[2:5]
	v_mfma_f32_16x16x32_bf16 v[54:57], v[170:173], v[208:211], v[54:57]
	v_mfma_f32_16x16x32_bf16 v[50:53], v[182:185], v[208:211], v[50:53]
	v_mfma_f32_16x16x32_bf16 v[38:41], v[170:173], v[216:219], v[38:41]
	v_mfma_f32_16x16x32_bf16 v[34:37], v[182:185], v[216:219], v[34:37]
	v_mfma_f32_16x16x32_bf16 v[22:25], v[170:173], v[224:227], v[22:25]
	v_mfma_f32_16x16x32_bf16 v[18:21], v[182:185], v[224:227], v[18:21]
	v_mfma_f32_16x16x32_bf16 v[6:9], v[170:173], v[234:237], v[6:9]
	v_mfma_f32_16x16x32_bf16 v[2:5], v[182:185], v[234:237], v[2:5]
	s_setprio 0
	s_barrier
	s_add_i32 s50, 0, 0x18000
	s_add_i32 s51, 0, 0x1c000
	v_add_u32_e32 v156, s50, v178
	v_add_u32_e32 v181, s51, v178
	ds_read_b128 v[130:133], v156
	ds_read_b128 v[134:137], v156 offset:1024
	ds_read_b128 v[152:155], v156 offset:2048
	ds_read_b128 v[156:159], v156 offset:3072
	ds_read_b128 v[166:169], v181
	ds_read_b128 v[170:173], v181 offset:1024
	ds_read_b128 v[174:177], v181 offset:2048
	ds_read_b128 v[182:185], v181 offset:3072
	s_add_u32 s46, s46, s20
	s_addc_u32 s47, s47, s21
	s_mov_b32 m0, s14
	v_lshl_add_u64 v[248:249], s[46:47], 0, v[138:139]
	ds_read_b128 v[204:207], v180 offset:32768
	ds_read_b128 v[208:211], v180 offset:33792
	ds_read_b128 v[212:215], v180 offset:34816
	ds_read_b128 v[216:219], v180 offset:35840
	ds_read_b128 v[220:223], v180 offset:36864
	ds_read_b128 v[224:227], v180 offset:37888
	ds_read_b128 v[230:233], v180 offset:38912
	ds_read_b128 v[234:237], v180 offset:39936
	global_load_lds_dwordx4 v[248:249], off
	v_lshl_add_u64 v[248:249], s[46:47], 0, v[142:143]
	s_mov_b32 m0, s15
	s_nop 0
	global_load_lds_dwordx4 v[248:249], off
	s_waitcnt vmcnt(8)
	s_waitcnt lgkmcnt(0)
	s_barrier
	s_setprio 1
	s_waitcnt lgkmcnt(0)
	v_mfma_f32_16x16x32_bf16 v[126:129], v[130:133], v[204:207], v[126:129]
	v_mfma_f32_16x16x32_bf16 v[122:125], v[152:155], v[204:207], v[122:125]
	v_mfma_f32_16x16x32_bf16 v[110:113], v[130:133], v[212:215], v[110:113]
	v_mfma_f32_16x16x32_bf16 v[106:109], v[152:155], v[212:215], v[106:109]
	v_mfma_f32_16x16x32_bf16 v[94:97], v[130:133], v[220:223], v[94:97]
	v_mfma_f32_16x16x32_bf16 v[90:93], v[152:155], v[220:223], v[90:93]
	v_mfma_f32_16x16x32_bf16 v[78:81], v[130:133], v[230:233], v[78:81]
	v_mfma_f32_16x16x32_bf16 v[74:77], v[152:155], v[230:233], v[74:77]
	v_mfma_f32_16x16x32_bf16 v[126:129], v[134:137], v[208:211], v[126:129]
	v_mfma_f32_16x16x32_bf16 v[122:125], v[156:159], v[208:211], v[122:125]
	v_mfma_f32_16x16x32_bf16 v[110:113], v[134:137], v[216:219], v[110:113]
	v_mfma_f32_16x16x32_bf16 v[106:109], v[156:159], v[216:219], v[106:109]
	v_mfma_f32_16x16x32_bf16 v[94:97], v[134:137], v[224:227], v[94:97]
	v_mfma_f32_16x16x32_bf16 v[90:93], v[156:159], v[224:227], v[90:93]
	v_mfma_f32_16x16x32_bf16 v[78:81], v[134:137], v[234:237], v[78:81]
	v_mfma_f32_16x16x32_bf16 v[74:77], v[156:159], v[234:237], v[74:77]
	s_setprio 0
	s_setprio 1
	v_mfma_f32_16x16x32_bf16 v[118:121], v[166:169], v[204:207], v[118:121]
	v_mfma_f32_16x16x32_bf16 v[114:117], v[174:177], v[204:207], v[114:117]
	v_mfma_f32_16x16x32_bf16 v[102:105], v[166:169], v[212:215], v[102:105]
	v_mfma_f32_16x16x32_bf16 v[98:101], v[174:177], v[212:215], v[98:101]
	v_mfma_f32_16x16x32_bf16 v[86:89], v[166:169], v[220:223], v[86:89]
	v_mfma_f32_16x16x32_bf16 v[82:85], v[174:177], v[220:223], v[82:85]
	v_mfma_f32_16x16x32_bf16 v[70:73], v[166:169], v[230:233], v[70:73]
	v_mfma_f32_16x16x32_bf16 v[66:69], v[174:177], v[230:233], v[66:69]
	v_mfma_f32_16x16x32_bf16 v[118:121], v[170:173], v[208:211], v[118:121]
	v_mfma_f32_16x16x32_bf16 v[114:117], v[182:185], v[208:211], v[114:117]
	v_mfma_f32_16x16x32_bf16 v[102:105], v[170:173], v[216:219], v[102:105]
	v_mfma_f32_16x16x32_bf16 v[98:101], v[182:185], v[216:219], v[98:101]
	v_mfma_f32_16x16x32_bf16 v[86:89], v[170:173], v[224:227], v[86:89]
	v_mfma_f32_16x16x32_bf16 v[82:85], v[182:185], v[224:227], v[82:85]
	v_mfma_f32_16x16x32_bf16 v[70:73], v[170:173], v[234:237], v[70:73]
	v_mfma_f32_16x16x32_bf16 v[66:69], v[182:185], v[234:237], v[66:69]
	s_setprio 0
	s_barrier
; #define PG8_STAGE(bufoff, gbase, voff) do { _Pragma("unroll") for (int _i = 0; _i < 2; ++_i) \
;     __builtin_amdgcn_global_load_lds((const unsigned*)((const char*)(gbase) + (voff)[_i]), (LAS unsigned*)(lds + (bufoff) + ldsw + _i * 8192), 16, 0, 0); } while (0)
; #define PG8_LDA(dst, b, h) do { _Pragma("unroll") for (int m = 0; m < 4; ++m) _Pragma("unroll") for (int k = 0; k < 2; ++k) dst[m][k] = *(const LAS bf16x8*)(lds + PG8_SA(b, h) + aoff + m * 2048 + k * 1024); } while (0)
; #define PG8_MMA(ai, bj, At, Bt) do { __builtin_amdgcn_s_setprio(1); _Pragma("unroll") for (int m = 0; m < 4; ++m) _Pragma("unroll") for (int n = 0; n < 2; ++n) _Pragma("unroll") for (int k = 0; k < 2; ++k) \
;     acc[ai][bj][m][n] = __builtin_amdgcn_mfma_f32_16x16x32_bf16(Bt[n][k], At[m][k], acc[ai][bj][m][n], 0, 0, 0); __builtin_amdgcn_s_setprio(0); } while (0)
; #define PG8_WAIT_V(n) asm volatile("s_waitcnt vmcnt(" #n ")" ::: "memory")
; #define PG8_WAIT_L(n) asm volatile("s_waitcnt lgkmcnt(" #n ")" ::: "memory")
; #define PG8_BAR __builtin_amdgcn_s_barrier()
; #define PG8_SCHED __builtin_amdgcn_sched_barrier(0)
; template <class Epi>
; DI void gemm_phase(LAS unsigned char* lds, const Gemm g, const StaticOrder& S, const Epi& E) {
;     ...
;     for (int t = 0; t < nt; t += 2) {
;       const bool last = (t == nt - 2);
;       const char* a1 = cA + (size_t)(t + 1) * kstep;
;       const char* a2 = last ? nA : cA + (size_t)(t + 2) * kstep; const char* b2 = last ? nB : cB + (size_t)(t + 2) * kstep;
;       const char* a3 = a2 + kstep; const char* b3 = b2 + kstep;
;     ...
;       PG8_LDA(At, 1, 1); PG8_STAGE(PG8_SB(1, 0), b3, voffB); PG8_STAGE(PG8_SB(1, 1), b3 + hstepB, voffB); PG8_STAGE(PG8_SA(1, 0), a3, voffA);
;       PG8_WAIT_V(8); PG8_WAIT_L(0); PG8_BAR; PG8_MMA(1, 0, At, B0); PG8_MMA(1, 1, At, B1); PG8_BAR; PG8_SCHED;
	s_add_i32 s46, s50, s17
	v_lshl_add_u64 v[160:161], v[160:161], 0, s[38:39]
	s_mov_b32 m0, s46
	ds_read_b128 v[204:207], v180 offset:49152
	ds_read_b128 v[208:211], v180 offset:50176
	ds_read_b128 v[212:215], v180 offset:51200
	ds_read_b128 v[216:219], v180 offset:52224
	ds_read_b128 v[220:223], v180 offset:53248
	ds_read_b128 v[224:227], v180 offset:54272
	ds_read_b128 v[230:233], v180 offset:55296
	ds_read_b128 v[234:237], v180 offset:56320
	global_load_lds_dwordx4 v[160:161], off
	v_lshl_add_u64 v[160:161], v[238:239], 0, s[38:39]
	s_add_i32 m0, s46, 0x2000
	s_add_i32 s46, s51, s17
	global_load_lds_dwordx4 v[160:161], off
	v_lshl_add_u64 v[160:161], v[240:241], 0, s[38:39]
	s_mov_b32 m0, s46
	s_nop 0
	global_load_lds_dwordx4 v[160:161], off
	v_lshl_add_u64 v[160:161], v[242:243], 0, s[38:39]
	s_add_i32 m0, s46, 0x2000
	s_nop 0
	global_load_lds_dwordx4 v[160:161], off
	v_lshl_add_u64 v[160:161], v[244:245], 0, s[38:39]
	s_mov_b32 m0, s6
	s_nop 0
	global_load_lds_dwordx4 v[160:161], off
	v_lshl_add_u64 v[160:161], v[246:247], 0, s[38:39]
	s_mov_b32 m0, s7
	s_nop 0
	global_load_lds_dwordx4 v[160:161], off
	s_waitcnt vmcnt(8)
	s_waitcnt lgkmcnt(0)
	s_barrier
	s_setprio 1
	s_waitcnt lgkmcnt(0)
	v_mfma_f32_16x16x32_bf16 v[62:65], v[130:133], v[204:207], v[62:65]
	v_mfma_f32_16x16x32_bf16 v[58:61], v[152:155], v[204:207], v[58:61]
	v_mfma_f32_16x16x32_bf16 v[46:49], v[130:133], v[212:215], v[46:49]
	v_mfma_f32_16x16x32_bf16 v[42:45], v[152:155], v[212:215], v[42:45]
	v_mfma_f32_16x16x32_bf16 v[30:33], v[130:133], v[220:223], v[30:33]
	v_mfma_f32_16x16x32_bf16 v[26:29], v[152:155], v[220:223], v[26:29]
	v_mfma_f32_16x16x32_bf16 v[14:17], v[130:133], v[230:233], v[14:17]
	v_mfma_f32_16x16x32_bf16 v[10:13], v[152:155], v[230:233], v[10:13]
	v_mfma_f32_16x16x32_bf16 v[62:65], v[134:137], v[208:211], v[62:65]
	v_mfma_f32_16x16x32_bf16 v[58:61], v[156:159], v[208:211], v[58:61]
	v_mfma_f32_16x16x32_bf16 v[46:49], v[134:137], v[216:219], v[46:49]
	v_mfma_f32_16x16x32_bf16 v[42:45], v[156:159], v[216:219], v[42:45]
	v_mfma_f32_16x16x32_bf16 v[30:33], v[134:137], v[224:227], v[30:33]
	v_mfma_f32_16x16x32_bf16 v[26:29], v[156:159], v[224:227], v[26:29]
	v_mfma_f32_16x16x32_bf16 v[14:17], v[134:137], v[234:237], v[14:17]
	v_mfma_f32_16x16x32_bf16 v[10:13], v[156:159], v[234:237], v[10:13]
	s_setprio 0
	s_setprio 1
	v_mfma_f32_16x16x32_bf16 v[54:57], v[166:169], v[204:207], v[54:57]
	v_mfma_f32_16x16x32_bf16 v[50:53], v[174:177], v[204:207], v[50:53]
	v_mfma_f32_16x16x32_bf16 v[38:41], v[166:169], v[212:215], v[38:41]
	v_mfma_f32_16x16x32_bf16 v[34:37], v[174:177], v[212:215], v[34:37]
	v_mfma_f32_16x16x32_bf16 v[22:25], v[166:169], v[220:223], v[22:25]
	v_mfma_f32_16x16x32_bf16 v[18:21], v[174:177], v[220:223], v[18:21]
	v_mfma_f32_16x16x32_bf16 v[6:9], v[166:169], v[230:233], v[6:9]
	v_mfma_f32_16x16x32_bf16 v[2:5], v[174:177], v[230:233], v[2:5]
	v_mfma_f32_16x16x32_bf16 v[54:57], v[170:173], v[208:211], v[54:57]
	v_mfma_f32_16x16x32_bf16 v[50:53], v[182:185], v[208:211], v[50:53]
	v_mfma_f32_16x16x32_bf16 v[38:41], v[170:173], v[216:219], v[38:41]
	v_mfma_f32_16x16x32_bf16 v[34:37], v[182:185], v[216:219], v[34:37]
	v_mfma_f32_16x16x32_bf16 v[22:25], v[170:173], v[224:227], v[22:25]
	v_mfma_f32_16x16x32_bf16 v[18:21], v[182:185], v[224:227], v[18:21]
	v_mfma_f32_16x16x32_bf16 v[6:9], v[170:173], v[234:237], v[6:9]
	v_mfma_f32_16x16x32_bf16 v[2:5], v[182:185], v[234:237], v[2:5]
	s_setprio 0
	s_add_u32 s44, s44, 0x100
	s_addc_u32 s45, s45, 0
	s_add_u32 s23, s23, 0x100
	s_addc_u32 s48, s48, 0
	s_cmp_ge_i32 s49, s16
	s_mov_b32 s46, s49
	s_cbranch_scc1 .Lgx2
	s_add_i32 s49, s46, 2
	s_add_u32 s50, s44, 0x80
	s_addc_u32 s47, s45, 0
	s_add_i32 s52, 0, 0x10000
	s_cmp_eq_u32 s33, s46
	s_cselect_b32 s47, s13, s47
	s_cselect_b32 s46, s12, s50
	s_cselect_b32 s51, s85, s48
	s_cselect_b32 s50, s84, s23
	s_add_i32 s53, 0, 0x14000
	s_branch .Lgr2
.Lgx2:
	s_barrier
.LBB0_845:
	v_readlane_b32 s44, v250, 50
	v_readlane_b32 s45, v250, 51
	s_and_b64 vcc, exec, s[44:45]
	s_cbranch_vccz .LBB0_847
	s_barrier
